# combined: GEMM epilogue (rstd preload, streamlined PLAIN path, batched GATE/COMBINE aux loads) + attention prompt loop rewrite (stagger, deeper prefetch, up-front K reads, ILP softmax)
# speedup vs baseline: 1.0067x; 1.0067x over previous
;     __device__ __forceinline__ void operator()(const f32x4 (&acc)[2][2][4][2], const Unit& u, int wr, int wc, int fr, int fq) const {
;     ...
;         const int row0 = u.pm * BM + wr * 64 + fr;
;         const int col0 = colt + wc * 32 + 8 * fq;
;         bf16_t* base = (bf16_t*)(ws + ob); const bf16_t* aux1 = (const bf16_t*)(ws + WS_R1); const bf16_t* aux2 = (const bf16_t*)(ws + WS_R2);
;         const float* rsp = (const float*)(ws + oRS);
;         if (k == EK_PAIRMUL || k == EK_SWIGLU) {
; #pragma unroll
;             for (int ai = 0; ai < 2; ++ai)
; #pragma unroll
;                 for (int m = 0; m < 4; ++m) {
;                     bf16_t* rowp = base + (size_t)(row0 + ai * HALF + m * 16) * ld + col0;
;                     const float rr = use_rs ? rsp[row0 + ai * HALF + m * 16] : 1.f;
;     ...
;                     const float rr = use_rs ? rsp[row0 + ai * HALF + m * 16] : 1.f;
.LBB0_714:
	s_add_u32 s40, s82, s8
	v_lshl_add_u32 v140, s25, 8, v160
	v_add_u32_e32 v142, s31, v168
	s_addc_u32 s41, s83, s9
	s_add_i32 s8, s36, -1
	s_cmp_lt_u32 s8, 2
	v_ashrrev_i32_e32 v143, 31, v142
	s_mov_b64 s[8:9], -1
	v_ashrrev_i32_e32 v141, 31, v140
	s_cselect_b64 s[30:31], -1, 0
	s_cmp_eq_u32 s75, 1
	s_cbranch_scc1 .Lepi_rs_load
	s_cmp_eq_u32 s75, 15
	s_cbranch_scc1 .Lepi_rs_load
	v_mov_b32_e32 v182, 1.0
	v_mov_b32_e32 v183, 1.0
	v_mov_b32_e32 v184, 1.0
	v_mov_b32_e32 v185, 1.0
	v_mov_b32_e32 v186, 1.0
	v_mov_b32_e32 v187, 1.0
	v_mov_b32_e32 v188, 1.0
	v_mov_b32_e32 v189, 1.0
	s_branch .Lepi_rs_done

; __device__ __forceinline__ float sigm(float x) { return __builtin_amdgcn_rcpf(1.0f + __builtin_amdgcn_exp2f(-1.4426950408889634f * x)); }
; __device__ __forceinline__ float bflo(unsigned w) { return __uint_as_float(w << 16); }
; __device__ __forceinline__ float bfhi(unsigned w) { return __uint_as_float(w & 0xffff0000u); }
; __device__ __forceinline__ float bflo(unsigned w) { return __uint_as_float(w << 16); }
; __device__ __forceinline__ float bfhi(unsigned w) { return __uint_as_float(w & 0xffff0000u); }
;     __device__ __forceinline__ void operator()(const f32x4 (&acc)[2][2][4][2], const Unit& u, int wr, int wc, int fr, int fq) const {
;     ...
;         if (k == EK_PAIRMUL || k == EK_SWIGLU) {
; #pragma unroll
;     ...
;                         if (k == EK_PLAIN) { v0 = v0 * (sc * rr); v1 = v1 * (sc * rr); }
;                         else if (k == EK_SIGMOID) {
; #pragma unroll
;                             for (int i = 0; i < 4; ++i) { v0[i] = sigm(v0[i] * rr); v1[i] = sigm(v1[i] * rr); }
;                         } else if (k == EK_GATE) {
;                             const u32x4e g = *(const u32x4e*)(aux1 + off);
;                             v0[0] *= bflo(g.x); v0[1] *= bfhi(g.x); v0[2] *= bflo(g.y); v0[3] *= bfhi(g.y);
;                             v1[0] *= bflo(g.z); v1[1] *= bfhi(g.z); v1[2] *= bflo(g.w); v1[3] *= bfhi(g.w);
;                         } else {
;                             const u32x4e y = *(const u32x4e*)(aux1 + off); const u32x4e g = *(const u32x4e*)(aux2 + off);
.Lepi_rs_done:
	s_cmp_eq_u32 s36, 4
	s_cbranch_scc1 .Lepi_gate_fast
	s_cmp_eq_u32 s36, 5
	s_cbranch_scc1 .Lepi_comb_fast
	s_cmp_eq_u32 s36, 0
	s_cbranch_scc1 .Lepi_plain_fast
	s_and_b64 vcc, exec, s[30:31]
	s_cbranch_vccnz .LBB0_717
	s_cmp_lt_i32 s75, 15
	s_cbranch_scc1 .LBB0_720
	s_cmp_eq_u32 s75, 15
	s_cselect_b64 s[8:9], -1, 0
	s_cbranch_execz .LBB0_721
	s_branch .LBB0_722

; __device__ __forceinline__ unsigned cvt_pk_bf16(float lo, float hi) { unsigned r; asm volatile("v_cvt_pk_bf16_f32 %0, %1, %2" : "=v"(r) : "v"(lo), "v"(hi)); return r; }
;     __device__ __forceinline__ void operator()(const f32x4 (&acc)[2][2][4][2], const Unit& u, int wr, int wc, int fr, int fq) const {
;     ...
;                     const size_t roff = (size_t)(row0 + ai * HALF + m * 16) * ld + col0;
;                     const float rr = use_rs ? rsp[row0 + ai * HALF + m * 16] : 1.f;
; #pragma unroll
;                     for (int bj = 0; bj < 2; ++bj) {
;                         f32x4 v0 = acc[ai][bj][m][0], v1 = acc[ai][bj][m][1];
;                         const size_t off = roff + bj * HALF;
;                         if (k == EK_PLAIN) { v0 = v0 * (sc * rr); v1 = v1 * (sc * rr); }
;     ...
;                         u32x4e w; w.x = cvt_pk_bf16(v0[0], v0[1]); w.y = cvt_pk_bf16(v0[2], v0[3]); w.z = cvt_pk_bf16(v1[0], v1[1]); w.w = cvt_pk_bf16(v1[2], v1[3]);
;                         *(u32x4e*)(base + off) = w;
.Lepi_plain_fast:
	v_mad_i64_i32 v[148:149], s[8:9], s27, v140, v[142:143]
	s_lshl_b32 s16, s27, 5
	s_mov_b32 s17, 0
	s_mul_i32 s30, s27, 0xa0
	s_mov_b32 s31, 0
	v_lshl_add_u64 v[150:151], v[148:149], 1, s[40:41]
	v_mul_f32_e32 v146, s67, v182
	v_mov_b32_e32 v147, v146
	v_pk_mul_f32 v[126:127], v[126:127], v[146:147]
	v_pk_mul_f32 v[128:129], v[128:129], v[146:147]
	v_pk_mul_f32 v[122:123], v[122:123], v[146:147]
	v_pk_mul_f32 v[124:125], v[124:125], v[146:147]
	v_cvt_pk_bf16_f32 v172, v126, v127
	v_cvt_pk_bf16_f32 v173, v128, v129
	v_cvt_pk_bf16_f32 v174, v122, v123
	v_cvt_pk_bf16_f32 v175, v124, v125
	global_store_dwordx4 v[150:151], v[172:175], off
	v_pk_mul_f32 v[118:119], v[118:119], v[146:147]
	v_pk_mul_f32 v[120:121], v[120:121], v[146:147]
	v_pk_mul_f32 v[114:115], v[114:115], v[146:147]
	v_pk_mul_f32 v[116:117], v[116:117], v[146:147]
	v_cvt_pk_bf16_f32 v176, v118, v119
	v_cvt_pk_bf16_f32 v177, v120, v121
	v_cvt_pk_bf16_f32 v178, v114, v115
	v_cvt_pk_bf16_f32 v179, v116, v117
	global_store_dwordx4 v[150:151], v[176:179], off offset:256
	v_lshl_add_u64 v[150:151], v[150:151], 0, s[16:17]
	v_mul_f32_e32 v146, s67, v183
	v_mov_b32_e32 v147, v146
	v_pk_mul_f32 v[110:111], v[110:111], v[146:147]
	v_pk_mul_f32 v[112:113], v[112:113], v[146:147]
	v_pk_mul_f32 v[106:107], v[106:107], v[146:147]
	v_pk_mul_f32 v[108:109], v[108:109], v[146:147]
	v_cvt_pk_bf16_f32 v172, v110, v111
	v_cvt_pk_bf16_f32 v173, v112, v113
	v_cvt_pk_bf16_f32 v174, v106, v107
	v_cvt_pk_bf16_f32 v175, v108, v109
	global_store_dwordx4 v[150:151], v[172:175], off
	v_pk_mul_f32 v[102:103], v[102:103], v[146:147]
	v_pk_mul_f32 v[104:105], v[104:105], v[146:147]
	v_pk_mul_f32 v[98:99], v[98:99], v[146:147]
	v_pk_mul_f32 v[100:101], v[100:101], v[146:147]
	v_cvt_pk_bf16_f32 v176, v102, v103
	v_cvt_pk_bf16_f32 v177, v104, v105
	v_cvt_pk_bf16_f32 v178, v98, v99
	v_cvt_pk_bf16_f32 v179, v100, v101
	global_store_dwordx4 v[150:151], v[176:179], off offset:256
	v_lshl_add_u64 v[150:151], v[150:151], 0, s[16:17]
	v_mul_f32_e32 v146, s67, v184
	v_mov_b32_e32 v147, v146
	v_pk_mul_f32 v[94:95], v[94:95], v[146:147]
	v_pk_mul_f32 v[96:97], v[96:97], v[146:147]
	v_pk_mul_f32 v[90:91], v[90:91], v[146:147]
	v_pk_mul_f32 v[92:93], v[92:93], v[146:147]
	v_cvt_pk_bf16_f32 v172, v94, v95
	v_cvt_pk_bf16_f32 v173, v96, v97
	v_cvt_pk_bf16_f32 v174, v90, v91
	v_cvt_pk_bf16_f32 v175, v92, v93
	global_store_dwordx4 v[150:151], v[172:175], off
	v_pk_mul_f32 v[86:87], v[86:87], v[146:147]
	v_pk_mul_f32 v[88:89], v[88:89], v[146:147]
	v_pk_mul_f32 v[82:83], v[82:83], v[146:147]
	v_pk_mul_f32 v[84:85], v[84:85], v[146:147]
	v_cvt_pk_bf16_f32 v176, v86, v87
	v_cvt_pk_bf16_f32 v177, v88, v89
	v_cvt_pk_bf16_f32 v178, v82, v83
	v_cvt_pk_bf16_f32 v179, v84, v85
	global_store_dwordx4 v[150:151], v[176:179], off offset:256
	v_lshl_add_u64 v[150:151], v[150:151], 0, s[16:17]
	v_mul_f32_e32 v146, s67, v185
	v_mov_b32_e32 v147, v146
	v_pk_mul_f32 v[78:79], v[78:79], v[146:147]
	v_pk_mul_f32 v[80:81], v[80:81], v[146:147]
	v_pk_mul_f32 v[74:75], v[74:75], v[146:147]
	v_pk_mul_f32 v[76:77], v[76:77], v[146:147]
	v_cvt_pk_bf16_f32 v172, v78, v79
	v_cvt_pk_bf16_f32 v173, v80, v81
	v_cvt_pk_bf16_f32 v174, v74, v75
	v_cvt_pk_bf16_f32 v175, v76, v77
	global_store_dwordx4 v[150:151], v[172:175], off
	v_pk_mul_f32 v[70:71], v[70:71], v[146:147]
	v_pk_mul_f32 v[72:73], v[72:73], v[146:147]
	v_pk_mul_f32 v[66:67], v[66:67], v[146:147]
	v_pk_mul_f32 v[68:69], v[68:69], v[146:147]
	v_cvt_pk_bf16_f32 v176, v70, v71
	v_cvt_pk_bf16_f32 v177, v72, v73
; __device__ __forceinline__ unsigned cvt_pk_bf16(float lo, float hi) { unsigned r; asm volatile("v_cvt_pk_bf16_f32 %0, %1, %2" : "=v"(r) : "v"(lo), "v"(hi)); return r; }
;     __device__ __forceinline__ void operator()(const f32x4 (&acc)[2][2][4][2], const Unit& u, int wr, int wc, int fr, int fq) const {
;     ...
;                     const size_t roff = (size_t)(row0 + ai * HALF + m * 16) * ld + col0;
;                     const float rr = use_rs ? rsp[row0 + ai * HALF + m * 16] : 1.f;
; #pragma unroll
;                     for (int bj = 0; bj < 2; ++bj) {
;                         f32x4 v0 = acc[ai][bj][m][0], v1 = acc[ai][bj][m][1];
;                         const size_t off = roff + bj * HALF;
;                         if (k == EK_PLAIN) { v0 = v0 * (sc * rr); v1 = v1 * (sc * rr); }
;     ...
;                         u32x4e w; w.x = cvt_pk_bf16(v0[0], v0[1]); w.y = cvt_pk_bf16(v0[2], v0[3]); w.z = cvt_pk_bf16(v1[0], v1[1]); w.w = cvt_pk_bf16(v1[2], v1[3]);
;                         *(u32x4e*)(base + off) = w;
	v_cvt_pk_bf16_f32 v178, v66, v67
	v_cvt_pk_bf16_f32 v179, v68, v69
	global_store_dwordx4 v[150:151], v[176:179], off offset:256
	v_lshl_add_u64 v[150:151], v[150:151], 0, s[30:31]
	v_mul_f32_e32 v146, s67, v186
	v_mov_b32_e32 v147, v146
	v_pk_mul_f32 v[60:61], v[60:61], v[146:147]
	v_pk_mul_f32 v[62:63], v[62:63], v[146:147]
	v_pk_mul_f32 v[56:57], v[56:57], v[146:147]
	v_pk_mul_f32 v[58:59], v[58:59], v[146:147]
	v_cvt_pk_bf16_f32 v172, v60, v61
	v_cvt_pk_bf16_f32 v173, v62, v63
	v_cvt_pk_bf16_f32 v174, v56, v57
	v_cvt_pk_bf16_f32 v175, v58, v59
	global_store_dwordx4 v[150:151], v[172:175], off
	v_pk_mul_f32 v[52:53], v[52:53], v[146:147]
	v_pk_mul_f32 v[54:55], v[54:55], v[146:147]
	v_pk_mul_f32 v[48:49], v[48:49], v[146:147]
	v_pk_mul_f32 v[50:51], v[50:51], v[146:147]
	v_cvt_pk_bf16_f32 v176, v52, v53
	v_cvt_pk_bf16_f32 v177, v54, v55
	v_cvt_pk_bf16_f32 v178, v48, v49
	v_cvt_pk_bf16_f32 v179, v50, v51
	global_store_dwordx4 v[150:151], v[176:179], off offset:256
	v_lshl_add_u64 v[150:151], v[150:151], 0, s[16:17]
	v_mul_f32_e32 v146, s67, v187
	v_mov_b32_e32 v147, v146
	v_pk_mul_f32 v[44:45], v[44:45], v[146:147]
	v_pk_mul_f32 v[46:47], v[46:47], v[146:147]
	v_pk_mul_f32 v[40:41], v[40:41], v[146:147]
	v_pk_mul_f32 v[42:43], v[42:43], v[146:147]
	v_cvt_pk_bf16_f32 v172, v44, v45
	v_cvt_pk_bf16_f32 v173, v46, v47
	v_cvt_pk_bf16_f32 v174, v40, v41
	v_cvt_pk_bf16_f32 v175, v42, v43
	global_store_dwordx4 v[150:151], v[172:175], off
	v_pk_mul_f32 v[36:37], v[36:37], v[146:147]
	v_pk_mul_f32 v[38:39], v[38:39], v[146:147]
	v_pk_mul_f32 v[32:33], v[32:33], v[146:147]
	v_pk_mul_f32 v[34:35], v[34:35], v[146:147]
	v_cvt_pk_bf16_f32 v176, v36, v37
	v_cvt_pk_bf16_f32 v177, v38, v39
	v_cvt_pk_bf16_f32 v178, v32, v33
	v_cvt_pk_bf16_f32 v179, v34, v35
	global_store_dwordx4 v[150:151], v[176:179], off offset:256
	v_lshl_add_u64 v[150:151], v[150:151], 0, s[16:17]
	v_mul_f32_e32 v146, s67, v188
	v_mov_b32_e32 v147, v146
	v_pk_mul_f32 v[28:29], v[28:29], v[146:147]
	v_pk_mul_f32 v[30:31], v[30:31], v[146:147]
	v_pk_mul_f32 v[24:25], v[24:25], v[146:147]
	v_pk_mul_f32 v[26:27], v[26:27], v[146:147]
	v_cvt_pk_bf16_f32 v172, v28, v29
	v_cvt_pk_bf16_f32 v173, v30, v31
	v_cvt_pk_bf16_f32 v174, v24, v25
	v_cvt_pk_bf16_f32 v175, v26, v27
	global_store_dwordx4 v[150:151], v[172:175], off
	v_pk_mul_f32 v[20:21], v[20:21], v[146:147]
	v_pk_mul_f32 v[22:23], v[22:23], v[146:147]
	v_pk_mul_f32 v[16:17], v[16:17], v[146:147]
	v_pk_mul_f32 v[18:19], v[18:19], v[146:147]
	v_cvt_pk_bf16_f32 v176, v20, v21
	v_cvt_pk_bf16_f32 v177, v22, v23
	v_cvt_pk_bf16_f32 v178, v16, v17
	v_cvt_pk_bf16_f32 v179, v18, v19
	global_store_dwordx4 v[150:151], v[176:179], off offset:256
	v_lshl_add_u64 v[150:151], v[150:151], 0, s[16:17]
	v_mul_f32_e32 v146, s67, v189
	v_mov_b32_e32 v147, v146
	v_pk_mul_f32 v[12:13], v[12:13], v[146:147]
	v_pk_mul_f32 v[14:15], v[14:15], v[146:147]
	v_pk_mul_f32 v[8:9], v[8:9], v[146:147]
	v_pk_mul_f32 v[10:11], v[10:11], v[146:147]
	v_cvt_pk_bf16_f32 v172, v12, v13
	v_cvt_pk_bf16_f32 v173, v14, v15
	v_cvt_pk_bf16_f32 v174, v8, v9
	v_cvt_pk_bf16_f32 v175, v10, v11
	global_store_dwordx4 v[150:151], v[172:175], off
	v_pk_mul_f32 v[4:5], v[4:5], v[146:147]
	v_pk_mul_f32 v[6:7], v[6:7], v[146:147]
	v_pk_mul_f32 v[0:1], v[0:1], v[146:147]
	v_pk_mul_f32 v[2:3], v[2:3], v[146:147]
	v_cvt_pk_bf16_f32 v176, v4, v5
	v_cvt_pk_bf16_f32 v177, v6, v7
	v_cvt_pk_bf16_f32 v178, v0, v1
	v_cvt_pk_bf16_f32 v179, v2, v3
	global_store_dwordx4 v[150:151], v[176:179], off offset:256
	s_branch .LBB0_967
